# attention: staggered wave halves (waves 4-7 run rotated loop: softmax+PV of previous tile then QK), 3-slot V ring in LDS
# speedup vs baseline: 1.0068x; 1.0019x over previous
.LBB0_39:
	s_lshl_b32 s0, s28, 7
	s_and_b32 s70, s0, 0x380000
	s_lshl_b32 s0, s28, 12
	s_and_b32 s1, s24, 7
	s_and_b32 s0, s0, 0x7000000
	s_lshl_b32 s1, s1, 9
	v_lshl_add_u64 v[210:211], v[196:197], 0, s[70:71]
	s_or_b32 s70, s1, s0
	s_lshl_b32 s0, s5, 8
	s_add_i32 s43, s0, s25
	s_lshl_b32 s1, s29, 9
	v_or_b32_e32 v208, s43, v189
	v_lshl_add_u64 v[212:213], s[70:71], 0, v[198:199]
	v_lshl_add_u64 v[214:215], s[70:71], 0, v[200:201]
	v_lshl_add_u64 v[216:217], s[70:71], 0, v[202:203]
	v_lshl_add_u64 v[218:219], s[70:71], 0, v[204:205]
	s_and_b32 s70, s1, 0x7000
	v_ashrrev_i32_e32 v209, 31, v208
	v_lshl_add_u64 v[206:207], v[208:209], 0, s[70:71]
	v_mov_b64_e32 v[0:1], s[14:15]
	s_and_b32 s42, s29, 7
	v_mad_u64_u32 v[0:1], s[38:39], v206, s10, v[0:1]
	v_mad_i32_i24 v1, v207, s10, v1
	s_mul_i32 s38, s42, 0x180
	s_mov_b32 s39, s71
	v_lshl_add_u64 v[0:1], v[0:1], 0, s[38:39]
	v_lshlrev_b64 v[20:21], 7, v[206:207]
	v_lshl_add_u64 v[4:5], v[0:1], 0, v[164:165]
	v_lshl_add_u64 v[34:35], v[192:193], 0, v[20:21]
	v_lshl_add_u64 v[20:21], v[194:195], 0, v[20:21]
	global_load_dwordx4 v[132:135], v[4:5], off
	global_load_dwordx4 v[128:131], v[4:5], off offset:32
	global_load_dwordx4 v[124:127], v[4:5], off offset:64
	global_load_dwordx4 v[116:119], v[4:5], off offset:96
	global_load_dwordx4 v[112:115], v[4:5], off offset:128
	global_load_dwordx4 v[104:107], v[4:5], off offset:160
	global_load_dwordx4 v[100:103], v[4:5], off offset:192
	global_load_dwordx4 v[96:99], v[4:5], off offset:224
	global_load_dwordx4 v[8:11], v[4:5], off offset:256
	global_load_dwordx4 v[0:3], v[4:5], off offset:288
	global_load_dwordx4 v[12:15], v[4:5], off offset:320
	s_nop 0
	global_load_dwordx4 v[4:7], v[4:5], off offset:352
	s_nop 0
	global_load_dwordx4 v[16:19], v[34:35], off offset:16
	global_load_dwordx4 v[22:25], v[34:35], off
	global_load_dwordx4 v[26:29], v[20:21], off offset:16
	global_load_dwordx4 v[30:33], v[20:21], off
	s_lshl_b32 s1, s70, 12
	s_add_u32 s1, s96, s1
	s_addc_u32 s5, s97, 0
	s_lshl_b32 s7, s42, 9
	s_add_u32 s38, s1, s7
	s_addc_u32 s39, s5, 0
	s_lshl_b32 s70, s70, 7
	s_or_b32 s44, s43, 31
	s_or_b32 s45, s0, 0xc0
	s_mov_b32 s46, 0
	v_mov_b32_e32 v209, 0
	v_mov_b32_e32 v247, 0xf149f2ca
	s_mov_b32 s13, 0
	s_waitcnt vmcnt(0)
	v_and_b32_e32 v37, 0xffff0000, v8
	v_lshlrev_b32_e32 v36, 16, v8
	s_waitcnt vmcnt(5)
	v_and_b32_e32 v39, 0xffff0000, v12
	v_lshlrev_b32_e32 v38, 16, v12
	v_lshlrev_b32_e32 v8, 16, v13
	s_waitcnt vmcnt(0)
	v_pk_mul_f32 v[40:41], v[30:31], v[36:37]
	v_pk_mul_f32 v[30:31], v[30:31], v[38:39]
	v_pk_fma_f32 v[40:41], v[22:23], v[38:39], v[40:41]
	v_pk_fma_f32 v[22:23], v[22:23], v[36:37], v[30:31] neg_lo:[0,0,1] neg_hi:[0,0,1]
	v_cvt_pk_bf16_f32 v108, v40, v41
	v_cvt_pk_bf16_f32 v120, v22, v23
	v_and_b32_e32 v23, 0xffff0000, v9
	v_lshlrev_b32_e32 v22, 16, v9
	v_and_b32_e32 v9, 0xffff0000, v13
	v_pk_mul_f32 v[12:13], v[32:33], v[22:23]
	s_nop 0
	v_pk_fma_f32 v[12:13], v[24:25], v[8:9], v[12:13]
	v_pk_mul_f32 v[8:9], v[32:33], v[8:9]
	v_cvt_pk_bf16_f32 v109, v12, v13
	v_pk_fma_f32 v[8:9], v[24:25], v[22:23], v[8:9] neg_lo:[0,0,1] neg_hi:[0,0,1]
	v_and_b32_e32 v13, 0xffff0000, v14
	v_cvt_pk_bf16_f32 v121, v8, v9
	v_and_b32_e32 v9, 0xffff0000, v10
	v_lshlrev_b32_e32 v8, 16, v10
	v_lshlrev_b32_e32 v12, 16, v14
	v_pk_mul_f32 v[22:23], v[26:27], v[8:9]
	v_lshlrev_b32_e32 v10, 16, v15
	v_pk_fma_f32 v[22:23], v[16:17], v[12:13], v[22:23]
	v_pk_mul_f32 v[12:13], v[26:27], v[12:13]
	v_cvt_pk_bf16_f32 v110, v22, v23
	v_pk_fma_f32 v[8:9], v[16:17], v[8:9], v[12:13] neg_lo:[0,0,1] neg_hi:[0,0,1]
	v_and_b32_e32 v25, 0xffff0000, v0
	v_cvt_pk_bf16_f32 v122, v8, v9
	v_and_b32_e32 v9, 0xffff0000, v11
	v_lshlrev_b32_e32 v8, 16, v11
	v_and_b32_e32 v11, 0xffff0000, v15
	v_pk_mul_f32 v[12:13], v[28:29], v[8:9]
	v_lshlrev_b32_e32 v24, 16, v0
	v_pk_fma_f32 v[12:13], v[18:19], v[10:11], v[12:13]
	v_pk_mul_f32 v[10:11], v[28:29], v[10:11]
	v_cvt_pk_bf16_f32 v111, v12, v13
	v_pk_fma_f32 v[8:9], v[18:19], v[8:9], v[10:11] neg_lo:[0,0,1] neg_hi:[0,0,1]
	v_and_b32_e32 v27, 0xffff0000, v4
	v_cvt_pk_bf16_f32 v123, v8, v9
	global_load_dwordx4 v[8:11], v[34:35], off offset:80
	global_load_dwordx4 v[16:19], v[34:35], off offset:64
	global_load_dwordx4 v[12:15], v[20:21], off offset:80
	s_nop 0
	global_load_dwordx4 v[20:23], v[20:21], off offset:64
	v_lshlrev_b32_e32 v26, 16, v4
	v_lshlrev_b32_e32 v0, 16, v5
	s_waitcnt vmcnt(0)
	v_pk_mul_f32 v[28:29], v[20:21], v[24:25]
	v_pk_mul_f32 v[20:21], v[20:21], v[26:27]
	v_pk_fma_f32 v[28:29], v[16:17], v[26:27], v[28:29]
	v_pk_fma_f32 v[16:17], v[16:17], v[24:25], v[20:21] neg_lo:[0,0,1] neg_hi:[0,0,1]
	v_cvt_pk_bf16_f32 v136, v28, v29
	v_cvt_pk_bf16_f32 v140, v16, v17
	v_and_b32_e32 v17, 0xffff0000, v1
	v_lshlrev_b32_e32 v16, 16, v1
	v_and_b32_e32 v1, 0xffff0000, v5
	v_pk_mul_f32 v[4:5], v[22:23], v[16:17]
	s_nop 0
	v_pk_fma_f32 v[4:5], v[18:19], v[0:1], v[4:5]
	v_pk_mul_f32 v[0:1], v[22:23], v[0:1]
	v_cvt_pk_bf16_f32 v137, v4, v5
	v_pk_fma_f32 v[0:1], v[18:19], v[16:17], v[0:1] neg_lo:[0,0,1] neg_hi:[0,0,1]
	v_and_b32_e32 v5, 0xffff0000, v6
	v_cvt_pk_bf16_f32 v141, v0, v1
	v_and_b32_e32 v1, 0xffff0000, v2
	v_lshlrev_b32_e32 v0, 16, v2
	v_lshlrev_b32_e32 v4, 16, v6
	v_pk_mul_f32 v[16:17], v[12:13], v[0:1]
	v_lshlrev_b32_e32 v2, 16, v7
	v_pk_fma_f32 v[16:17], v[8:9], v[4:5], v[16:17]
	v_pk_mul_f32 v[4:5], v[12:13], v[4:5]
	v_cvt_pk_bf16_f32 v138, v16, v17
	v_pk_fma_f32 v[0:1], v[8:9], v[0:1], v[4:5] neg_lo:[0,0,1] neg_hi:[0,0,1]
	v_lshl_add_u64 v[16:17], v[180:181], 1, s[38:39]
	v_cvt_pk_bf16_f32 v142, v0, v1
	v_and_b32_e32 v1, 0xffff0000, v3
	v_lshlrev_b32_e32 v0, 16, v3
	v_and_b32_e32 v3, 0xffff0000, v7
	v_pk_mul_f32 v[4:5], v[14:15], v[0:1]
	global_load_dwordx4 v[16:19], v[16:17], off offset:256
	v_pk_fma_f32 v[4:5], v[10:11], v[2:3], v[4:5]
	v_pk_mul_f32 v[2:3], v[14:15], v[2:3]
	v_cvt_pk_bf16_f32 v139, v4, v5
	v_pk_fma_f32 v[0:1], v[10:11], v[0:1], v[2:3] neg_lo:[0,0,1] neg_hi:[0,0,1]
	s_nop 0
	v_cvt_pk_bf16_f32 v143, v0, v1
	v_lshl_add_u64 v[0:1], v[180:181], 1, s[38:39]
	global_load_dwordx4 v[4:7], v[0:1], off
	v_lshl_add_u64 v[0:1], v[182:183], 1, s[38:39]
	global_load_dwordx4 v[8:11], v[0:1], off
	v_lshl_add_u64 v[0:1], v[190:191], 0, s[70:71]
	global_load_dwordx4 v[12:15], v[0:1], off
	v_lshl_add_u64 v[0:1], v[182:183], 1, s[38:39]
	global_load_dwordx4 v[0:3], v[0:1], off offset:256
	s_waitcnt vmcnt(0)
	ds_write_b128 v244, v[4:7]
	s_waitcnt vmcnt(2)
	ds_write_b128 v244, v[8:11] offset:12800
	s_waitcnt vmcnt(1)
	ds_write_b128 v245, v[12:15] offset:256
	v_mov_b32_e32 v14, v165
	v_mov_b32_e32 v15, v165
	s_waitcnt vmcnt(0)
	s_movk_i32 s0, 320
	s_movk_i32 s1, 1280
	v_lshrrev_b32_e32 v216, 4, v220
	v_mul_u32_u24_e32 v216, s0, v216
	v_and_b32_e32 v248, 15, v220
	v_lshl_add_u32 v216, v248, 4, v216
	v_and_b32_e32 v217, 3, v220
	v_lshlrev_b32_e32 v217, 3, v217
	v_bfe_u32 v248, v220, 2, 2
	v_mad_u32_u24 v217, v248, s0, v217
	v_bfe_u32 v248, v220, 4, 1
	v_lshl_add_u32 v217, v248, 5, v217
	v_bfe_u32 v248, v220, 5, 1
	v_mad_u32_u24 v217, v248, s1, v217
	ds_write_b128 v216, v[16:19] offset:51200
	ds_write_b128 v216, v[0:3] offset:61440
	v_mov_b32_e32 v0, v165
	v_mov_b32_e32 v1, v165
	v_mov_b32_e32 v2, v165
	v_mov_b32_e32 v3, v165
	v_mov_b32_e32 v4, v165
	v_mov_b32_e32 v5, v165
	v_mov_b32_e32 v6, v165
	v_mov_b32_e32 v7, v165
	v_mov_b32_e32 v8, v165
	v_mov_b32_e32 v9, v165
	v_mov_b32_e32 v10, v165
	v_mov_b32_e32 v11, v165
	v_mov_b32_e32 v12, v165
	v_mov_b32_e32 v13, v165
	v_mov_b64_e32 v[30:31], v[14:15]
	v_mov_b64_e32 v[46:47], v[14:15]
	v_mov_b64_e32 v[62:63], v[14:15]
	v_mov_b64_e32 v[28:29], v[12:13]
	v_mov_b64_e32 v[26:27], v[10:11]
	v_mov_b64_e32 v[24:25], v[8:9]
	v_mov_b64_e32 v[22:23], v[6:7]
	v_mov_b64_e32 v[20:21], v[4:5]
	v_mov_b64_e32 v[18:19], v[2:3]
	v_mov_b64_e32 v[16:17], v[0:1]
	v_mov_b64_e32 v[44:45], v[12:13]
	v_mov_b64_e32 v[42:43], v[10:11]
	v_mov_b64_e32 v[40:41], v[8:9]
	v_mov_b64_e32 v[38:39], v[6:7]
	v_mov_b64_e32 v[36:37], v[4:5]
	v_mov_b64_e32 v[34:35], v[2:3]
	v_mov_b64_e32 v[32:33], v[0:1]
	v_mov_b64_e32 v[60:61], v[12:13]
	v_mov_b64_e32 v[58:59], v[10:11]
	v_mov_b64_e32 v[56:57], v[8:9]
	v_mov_b64_e32 v[54:55], v[6:7]
	v_mov_b64_e32 v[52:53], v[4:5]
	v_mov_b64_e32 v[50:51], v[2:3]
	v_mov_b64_e32 v[48:49], v[0:1]
	s_waitcnt lgkmcnt(0)
	s_barrier
	v_lshl_add_u64 v[248:249], s[20:21], 0, v[212:213]
	global_load_dwordx4 v[152:155], v[248:249], off
	v_lshl_add_u64 v[170:171], s[20:21], 0, v[214:215]
	global_load_dwordx4 v[156:159], v[170:171], off
	v_lshl_add_u64 v[218:219], s[20:21], 0, v[210:211]
	global_load_dwordx4 v[160:163], v[218:219], off
	global_load_dwordx4 v[144:147], v[248:249], off offset:256
	global_load_dwordx4 v[148:151], v[170:171], off offset:256
	s_mov_b64 s[38:39], 0x2000
	v_lshl_add_u64 v[210:211], v[210:211], 0, s[38:39]
	v_lshl_add_u64 v[212:213], v[212:213], 0, s[72:73]
	v_lshl_add_u64 v[214:215], v[214:215], 0, s[72:73]
	s_cmp_ge_u32 s25, 128
	s_cbranch_scc1 .LatB_40
.LatA_40:
	s_cmp_le_i32 s46, s44
	s_cselect_b64 s[0:1], -1, 0
	s_cbranch_scc0 .LatA_noqk
	s_setprio 1
	s_and_b32 s5, s13, 1
	s_mul_i32 s7, s5, 0x6400
	v_add_u32_e32 v250, s7, v243
	ds_read_b128 v[166:169], v250
	ds_read_b128 v[172:175], v250 offset:12800
	ds_read_b128 v[176:179], v250 offset:32
	ds_read_b128 v[222:225], v250 offset:12832
	ds_read_b128 v[228:231], v250 offset:64
	ds_read_b128 v[232:235], v250 offset:12864
	s_waitcnt lgkmcnt(5)
	v_mfma_f32_32x32x16_bf16 v[64:79], v[166:169], v[132:135], 0
	ds_read_b128 v[166:169], v250 offset:96
	s_waitcnt lgkmcnt(5)
	v_mfma_f32_32x32x16_bf16 v[80:95], v[172:175], v[132:135], 0
	ds_read_b128 v[172:175], v250 offset:12896
	s_waitcnt lgkmcnt(5)
	v_mfma_f32_32x32x16_bf16 v[64:79], v[176:179], v[128:131], v[64:79]
	ds_read_b128 v[176:179], v250 offset:128
	s_waitcnt lgkmcnt(5)
	v_mfma_f32_32x32x16_bf16 v[80:95], v[222:225], v[128:131], v[80:95]
	ds_read_b128 v[222:225], v250 offset:12928
	s_waitcnt lgkmcnt(5)
	v_mfma_f32_32x32x16_bf16 v[64:79], v[228:231], v[124:127], v[64:79]
	ds_read_b128 v[228:231], v250 offset:160
	s_waitcnt lgkmcnt(5)
	v_mfma_f32_32x32x16_bf16 v[80:95], v[232:235], v[124:127], v[80:95]
	ds_read_b128 v[232:235], v250 offset:12960
	s_waitcnt lgkmcnt(5)
	v_mfma_f32_32x32x16_bf16 v[64:79], v[166:169], v[116:119], v[64:79]
	ds_read_b128 v[166:169], v250 offset:192
	s_waitcnt lgkmcnt(5)
	v_mfma_f32_32x32x16_bf16 v[80:95], v[172:175], v[116:119], v[80:95]
	ds_read_b128 v[172:175], v250 offset:12992
	s_waitcnt lgkmcnt(5)
	v_mfma_f32_32x32x16_bf16 v[64:79], v[176:179], v[112:115], v[64:79]
	ds_read_b128 v[176:179], v250 offset:224
	s_waitcnt lgkmcnt(5)
	v_mfma_f32_32x32x16_bf16 v[80:95], v[222:225], v[112:115], v[80:95]
	ds_read_b128 v[222:225], v250 offset:13024
	s_waitcnt lgkmcnt(5)
	v_mfma_f32_32x32x16_bf16 v[64:79], v[228:231], v[104:107], v[64:79]
	ds_read_b128 v[228:231], v250 offset:256
	s_waitcnt lgkmcnt(5)
	v_mfma_f32_32x32x16_bf16 v[80:95], v[232:235], v[104:107], v[80:95]
	ds_read_b128 v[232:235], v250 offset:13056
	s_waitcnt lgkmcnt(5)
	v_mfma_f32_32x32x16_bf16 v[64:79], v[166:169], v[100:103], v[64:79]
	ds_read_b128 v[166:169], v250 offset:288
	s_waitcnt lgkmcnt(5)
	v_mfma_f32_32x32x16_bf16 v[80:95], v[172:175], v[100:103], v[80:95]
	ds_read_b128 v[172:175], v250 offset:13088
	s_waitcnt lgkmcnt(5)
	v_mfma_f32_32x32x16_bf16 v[64:79], v[176:179], v[96:99], v[64:79]
	ds_read_b128 v[176:179], v250 offset:320
	s_waitcnt lgkmcnt(5)
	v_mfma_f32_32x32x16_bf16 v[80:95], v[222:225], v[96:99], v[80:95]
	ds_read_b128 v[222:225], v250 offset:13120
	s_waitcnt lgkmcnt(5)
	v_mfma_f32_32x32x16_bf16 v[64:79], v[228:231], v[120:123], v[64:79]
	ds_read_b128 v[228:231], v250 offset:352
	s_waitcnt lgkmcnt(5)
	v_mfma_f32_32x32x16_bf16 v[80:95], v[232:235], v[120:123], v[80:95]
	ds_read_b128 v[232:235], v250 offset:13152
	s_waitcnt lgkmcnt(5)
	v_mfma_f32_32x32x16_bf16 v[64:79], v[166:169], v[140:143], v[64:79]
	s_waitcnt lgkmcnt(4)
	v_mfma_f32_32x32x16_bf16 v[80:95], v[172:175], v[140:143], v[80:95]
	s_waitcnt lgkmcnt(3)
	v_mfma_f32_32x32x16_bf16 v[64:79], v[176:179], v[108:111], v[64:79]
	s_waitcnt lgkmcnt(2)
	v_mfma_f32_32x32x16_bf16 v[80:95], v[222:225], v[108:111], v[80:95]
	s_waitcnt lgkmcnt(1)
	v_mfma_f32_32x32x16_bf16 v[64:79], v[228:231], v[136:139], v[64:79]
	s_waitcnt lgkmcnt(0)
	v_mfma_f32_32x32x16_bf16 v[80:95], v[232:235], v[136:139], v[80:95]
	s_setprio 0
.LatA_noqk:
	s_cmp_eq_u32 s46, s45
	s_cbranch_scc1 .LatA_nostage
	s_and_b32 s5, s13, 1
	s_xor_b32 s7, s5, 1
	s_mul_i32 s9, s7, 0x6400
	v_add3_u32 v172, s9, v236, v237
	s_waitcnt vmcnt(4)
	ds_write_b128 v172, v[152:155]
	s_waitcnt vmcnt(3)
	ds_write_b128 v172, v[156:159] offset:12800
	v_add3_u32 v173, s9, v238, v239
	s_waitcnt vmcnt(2)
	ds_write_b128 v173, v[160:163] offset:256
	s_add_i32 s7, s13, 1
	s_mul_i32 s38, s7, 43
	s_lshr_b32 s38, s38, 7
	s_mul_i32 s38, s38, 3
	s_sub_i32 s7, s7, s38
	s_mul_i32 s7, s7, 20480
	v_add_u32_e32 v173, s7, v216
	s_waitcnt vmcnt(1)
	ds_write_b128 v173, v[144:147] offset:51200
	s_waitcnt vmcnt(0)
	ds_write_b128 v173, v[148:151] offset:61440
	s_add_i32 s7, s46, 64
	s_cmp_eq_u32 s7, s45
	s_cbranch_scc1 .LatA_nostage
	v_lshl_add_u64 v[248:249], s[20:21], 0, v[212:213]
	global_load_dwordx4 v[152:155], v[248:249], off
	v_lshl_add_u64 v[170:171], s[20:21], 0, v[214:215]
	global_load_dwordx4 v[156:159], v[170:171], off
	v_lshl_add_u64 v[218:219], s[20:21], 0, v[210:211]
	global_load_dwordx4 v[160:163], v[218:219], off
	global_load_dwordx4 v[144:147], v[248:249], off offset:256
	global_load_dwordx4 v[148:151], v[170:171], off offset:256
	s_mov_b64 s[38:39], 0x2000
	v_lshl_add_u64 v[210:211], v[210:211], 0, s[38:39]
	v_lshl_add_u64 v[212:213], v[212:213], 0, s[72:73]
	v_lshl_add_u64 v[214:215], v[214:215], 0, s[72:73]
.LatA_nostage:
	s_andn2_b64 vcc, exec, s[0:1]
	s_cbranch_vccnz .LatA_novis
	s_mov_b32 s5, s13
	s_mul_i32 s38, s5, 43
	s_lshr_b32 s38, s38, 7
	s_mul_i32 s38, s38, 3
	s_sub_i32 s5, s5, s38
	s_mul_i32 s5, s5, 20480
	s_add_i32 s5, s5, 51200
	v_add_u32_e32 v250, s5, v217
	ds_read_b64_tr_b16 v[166:167], v250 offset:0
	ds_read_b64_tr_b16 v[168:169], v250 offset:2560
	ds_read_b64_tr_b16 v[172:173], v250 offset:5120
	ds_read_b64_tr_b16 v[174:175], v250 offset:7680
	ds_read_b64_tr_b16 v[176:177], v250 offset:10240
	ds_read_b64_tr_b16 v[178:179], v250 offset:12800
	ds_read_b64_tr_b16 v[222:223], v250 offset:15360
	ds_read_b64_tr_b16 v[224:225], v250 offset:17920
	ds_read_b64_tr_b16 v[228:229], v250 offset:64
	ds_read_b64_tr_b16 v[230:231], v250 offset:2624
	ds_read_b64_tr_b16 v[232:233], v250 offset:5184
	ds_read_b64_tr_b16 v[234:235], v250 offset:7744
	s_sub_i32 s9, s46, 0
	s_add_i32 s0, s9, 63
	s_cmp_gt_i32 s0, s43
	s_cbranch_scc0 .LatA_fast
	v_sub_u32_e32 v227, v208, v188
	v_subrev_u32_e32 v227, s9, v227
	v_cmp_gt_i32_e32 vcc, 0, v227
	v_cmp_gt_i32_e64 s[0:1], 1, v227
	v_cmp_gt_i32_e64 s[38:39], 2, v227
	v_cndmask_b32_e32 v64, v64, v226, vcc
	v_cmp_gt_i32_e32 vcc, 3, v227
	v_cndmask_b32_e64 v65, v65, v226, s[0:1]
	v_cmp_gt_i32_e64 s[0:1], 8, v227
	v_cndmask_b32_e64 v66, v66, v226, s[38:39]
	v_cmp_gt_i32_e64 s[38:39], 9, v227
	v_cndmask_b32_e32 v67, v67, v226, vcc
	v_cmp_gt_i32_e32 vcc, 10, v227
	v_cndmask_b32_e64 v68, v68, v226, s[0:1]
	v_cmp_gt_i32_e64 s[0:1], 11, v227
	v_cndmask_b32_e64 v69, v69, v226, s[38:39]
	v_cmp_gt_i32_e64 s[38:39], 16, v227
	v_cndmask_b32_e32 v70, v70, v226, vcc
	v_cmp_gt_i32_e32 vcc, 17, v227
	v_cndmask_b32_e64 v71, v71, v226, s[0:1]
	v_cmp_gt_i32_e64 s[0:1], 18, v227
	v_cndmask_b32_e64 v72, v72, v226, s[38:39]
	v_cmp_gt_i32_e64 s[38:39], 19, v227
	v_cndmask_b32_e32 v73, v73, v226, vcc
	v_cmp_gt_i32_e32 vcc, 24, v227
	v_cndmask_b32_e64 v74, v74, v226, s[0:1]
	v_cmp_gt_i32_e64 s[0:1], 25, v227
	v_cndmask_b32_e64 v75, v75, v226, s[38:39]
	v_cmp_gt_i32_e64 s[38:39], 26, v227
	v_cndmask_b32_e32 v76, v76, v226, vcc
	v_cmp_gt_i32_e32 vcc, 27, v227
	v_cndmask_b32_e64 v77, v77, v226, s[0:1]
	v_cmp_gt_i32_e64 s[0:1], 32, v227
	v_cndmask_b32_e64 v78, v78, v226, s[38:39]
	v_cmp_gt_i32_e64 s[38:39], 33, v227
	v_cndmask_b32_e32 v79, v79, v226, vcc
	v_cmp_gt_i32_e32 vcc, 34, v227
	v_cndmask_b32_e64 v80, v80, v226, s[0:1]
	v_cmp_gt_i32_e64 s[0:1], 35, v227
	v_cndmask_b32_e64 v81, v81, v226, s[38:39]
	v_cmp_gt_i32_e64 s[38:39], 40, v227
	v_cndmask_b32_e32 v82, v82, v226, vcc
	v_cmp_gt_i32_e32 vcc, 41, v227
	v_cndmask_b32_e64 v83, v83, v226, s[0:1]
	v_cmp_gt_i32_e64 s[0:1], 42, v227
	v_cndmask_b32_e64 v84, v84, v226, s[38:39]
	v_cmp_gt_i32_e64 s[38:39], 43, v227
	v_cndmask_b32_e32 v85, v85, v226, vcc
	v_cmp_gt_i32_e32 vcc, 48, v227
	v_cndmask_b32_e64 v86, v86, v226, s[0:1]
	v_cmp_gt_i32_e64 s[0:1], 49, v227
	v_cndmask_b32_e64 v87, v87, v226, s[38:39]
	v_cmp_gt_i32_e64 s[38:39], 50, v227
	v_cndmask_b32_e32 v88, v88, v226, vcc
	v_cmp_gt_i32_e32 vcc, 51, v227
	v_cndmask_b32_e64 v89, v89, v226, s[0:1]
	v_cmp_gt_i32_e64 s[0:1], 56, v227
	v_cndmask_b32_e64 v90, v90, v226, s[38:39]
	v_cmp_gt_i32_e64 s[38:39], 57, v227
	v_cndmask_b32_e32 v91, v91, v226, vcc
	v_cmp_gt_i32_e32 vcc, 58, v227
	v_cndmask_b32_e64 v92, v92, v226, s[0:1]
	v_cmp_gt_i32_e64 s[0:1], 59, v227
	v_cndmask_b32_e64 v93, v93, v226, s[38:39]
	s_nop 1
	v_cndmask_b32_e32 v94, v94, v226, vcc
	v_cndmask_b32_e64 v95, v95, v226, s[0:1]

.LatB_40:
	s_cmp_eq_u32 s46, 0
	s_cbranch_scc1 .LatB_noprev
	s_sub_i32 s0, s46, 64
	s_cmp_le_i32 s0, s44
	s_cbranch_scc0 .LatB_noprev
	s_add_i32 s5, s13, -1
	s_mul_i32 s38, s5, 43
	s_lshr_b32 s38, s38, 7
	s_mul_i32 s38, s38, 3
	s_sub_i32 s5, s5, s38
	s_mul_i32 s5, s5, 20480
	s_add_i32 s5, s5, 51200
	v_add_u32_e32 v250, s5, v217
	ds_read_b64_tr_b16 v[166:167], v250 offset:0
	ds_read_b64_tr_b16 v[168:169], v250 offset:2560
	ds_read_b64_tr_b16 v[172:173], v250 offset:5120
	ds_read_b64_tr_b16 v[174:175], v250 offset:7680
	ds_read_b64_tr_b16 v[176:177], v250 offset:10240
	ds_read_b64_tr_b16 v[178:179], v250 offset:12800
	ds_read_b64_tr_b16 v[222:223], v250 offset:15360
	ds_read_b64_tr_b16 v[224:225], v250 offset:17920
	ds_read_b64_tr_b16 v[228:229], v250 offset:64
	ds_read_b64_tr_b16 v[230:231], v250 offset:2624
	ds_read_b64_tr_b16 v[232:233], v250 offset:5184
	ds_read_b64_tr_b16 v[234:235], v250 offset:7744
	s_sub_i32 s9, s46, 64
	s_add_i32 s0, s9, 63
	s_cmp_gt_i32 s0, s43
	s_cbranch_scc0 .LatBp_fast
	v_sub_u32_e32 v227, v208, v188
	v_subrev_u32_e32 v227, s9, v227
	v_cmp_gt_i32_e32 vcc, 0, v227
	v_cmp_gt_i32_e64 s[0:1], 1, v227
	v_cmp_gt_i32_e64 s[38:39], 2, v227
	v_cndmask_b32_e32 v64, v64, v226, vcc
	v_cmp_gt_i32_e32 vcc, 3, v227
	v_cndmask_b32_e64 v65, v65, v226, s[0:1]
	v_cmp_gt_i32_e64 s[0:1], 8, v227
	v_cndmask_b32_e64 v66, v66, v226, s[38:39]
	v_cmp_gt_i32_e64 s[38:39], 9, v227
	v_cndmask_b32_e32 v67, v67, v226, vcc
	v_cmp_gt_i32_e32 vcc, 10, v227
	v_cndmask_b32_e64 v68, v68, v226, s[0:1]
	v_cmp_gt_i32_e64 s[0:1], 11, v227
	v_cndmask_b32_e64 v69, v69, v226, s[38:39]
	v_cmp_gt_i32_e64 s[38:39], 16, v227
	v_cndmask_b32_e32 v70, v70, v226, vcc
	v_cmp_gt_i32_e32 vcc, 17, v227
	v_cndmask_b32_e64 v71, v71, v226, s[0:1]
	v_cmp_gt_i32_e64 s[0:1], 18, v227
	v_cndmask_b32_e64 v72, v72, v226, s[38:39]
	v_cmp_gt_i32_e64 s[38:39], 19, v227
	v_cndmask_b32_e32 v73, v73, v226, vcc
	v_cmp_gt_i32_e32 vcc, 24, v227
	v_cndmask_b32_e64 v74, v74, v226, s[0:1]
	v_cmp_gt_i32_e64 s[0:1], 25, v227
	v_cndmask_b32_e64 v75, v75, v226, s[38:39]
	v_cmp_gt_i32_e64 s[38:39], 26, v227
	v_cndmask_b32_e32 v76, v76, v226, vcc
	v_cmp_gt_i32_e32 vcc, 27, v227
	v_cndmask_b32_e64 v77, v77, v226, s[0:1]
	v_cmp_gt_i32_e64 s[0:1], 32, v227
	v_cndmask_b32_e64 v78, v78, v226, s[38:39]
	v_cmp_gt_i32_e64 s[38:39], 33, v227
	v_cndmask_b32_e32 v79, v79, v226, vcc
	v_cmp_gt_i32_e32 vcc, 34, v227
	v_cndmask_b32_e64 v80, v80, v226, s[0:1]
	v_cmp_gt_i32_e64 s[0:1], 35, v227
	v_cndmask_b32_e64 v81, v81, v226, s[38:39]
	v_cmp_gt_i32_e64 s[38:39], 40, v227
	v_cndmask_b32_e32 v82, v82, v226, vcc
	v_cmp_gt_i32_e32 vcc, 41, v227
	v_cndmask_b32_e64 v83, v83, v226, s[0:1]
	v_cmp_gt_i32_e64 s[0:1], 42, v227
	v_cndmask_b32_e64 v84, v84, v226, s[38:39]
	v_cmp_gt_i32_e64 s[38:39], 43, v227
	v_cndmask_b32_e32 v85, v85, v226, vcc
	v_cmp_gt_i32_e32 vcc, 48, v227
	v_cndmask_b32_e64 v86, v86, v226, s[0:1]
	v_cmp_gt_i32_e64 s[0:1], 49, v227
	v_cndmask_b32_e64 v87, v87, v226, s[38:39]
	v_cmp_gt_i32_e64 s[38:39], 50, v227
	v_cndmask_b32_e32 v88, v88, v226, vcc
	v_cmp_gt_i32_e32 vcc, 51, v227
	v_cndmask_b32_e64 v89, v89, v226, s[0:1]
	v_cmp_gt_i32_e64 s[0:1], 56, v227
	v_cndmask_b32_e64 v90, v90, v226, s[38:39]
	v_cmp_gt_i32_e64 s[38:39], 57, v227
	v_cndmask_b32_e32 v91, v91, v226, vcc
	v_cmp_gt_i32_e32 vcc, 58, v227
	v_cndmask_b32_e64 v92, v92, v226, s[0:1]
	v_cmp_gt_i32_e64 s[0:1], 59, v227
	v_cndmask_b32_e64 v93, v93, v226, s[38:39]
	s_nop 1
	v_cndmask_b32_e32 v94, v94, v226, vcc
	v_cndmask_b32_e64 v95, v95, v226, s[0:1]

.LatB_noprev:
	s_cmp_le_i32 s46, s44
	s_cbranch_scc0 .LatB_noqk
	s_setprio 1
	s_and_b32 s5, s13, 1
	s_mul_i32 s7, s5, 0x6400
	v_add_u32_e32 v250, s7, v243
	ds_read_b128 v[166:169], v250
	ds_read_b128 v[172:175], v250 offset:12800
	ds_read_b128 v[176:179], v250 offset:32
	ds_read_b128 v[222:225], v250 offset:12832
	ds_read_b128 v[228:231], v250 offset:64
	ds_read_b128 v[232:235], v250 offset:12864
	s_waitcnt lgkmcnt(5)
	v_mfma_f32_32x32x16_bf16 v[64:79], v[166:169], v[132:135], 0
	ds_read_b128 v[166:169], v250 offset:96
	s_waitcnt lgkmcnt(5)
	v_mfma_f32_32x32x16_bf16 v[80:95], v[172:175], v[132:135], 0
	ds_read_b128 v[172:175], v250 offset:12896
	s_waitcnt lgkmcnt(5)
	v_mfma_f32_32x32x16_bf16 v[64:79], v[176:179], v[128:131], v[64:79]
	ds_read_b128 v[176:179], v250 offset:128
	s_waitcnt lgkmcnt(5)
	v_mfma_f32_32x32x16_bf16 v[80:95], v[222:225], v[128:131], v[80:95]
	ds_read_b128 v[222:225], v250 offset:12928
	s_waitcnt lgkmcnt(5)
	v_mfma_f32_32x32x16_bf16 v[64:79], v[228:231], v[124:127], v[64:79]
	ds_read_b128 v[228:231], v250 offset:160
	s_waitcnt lgkmcnt(5)
	v_mfma_f32_32x32x16_bf16 v[80:95], v[232:235], v[124:127], v[80:95]
	ds_read_b128 v[232:235], v250 offset:12960
	s_waitcnt lgkmcnt(5)
	v_mfma_f32_32x32x16_bf16 v[64:79], v[166:169], v[116:119], v[64:79]
	ds_read_b128 v[166:169], v250 offset:192
	s_waitcnt lgkmcnt(5)
	v_mfma_f32_32x32x16_bf16 v[80:95], v[172:175], v[116:119], v[80:95]
	ds_read_b128 v[172:175], v250 offset:12992
	s_waitcnt lgkmcnt(5)
	v_mfma_f32_32x32x16_bf16 v[64:79], v[176:179], v[112:115], v[64:79]
	ds_read_b128 v[176:179], v250 offset:224
	s_waitcnt lgkmcnt(5)
	v_mfma_f32_32x32x16_bf16 v[80:95], v[222:225], v[112:115], v[80:95]
	ds_read_b128 v[222:225], v250 offset:13024
	s_waitcnt lgkmcnt(5)
	v_mfma_f32_32x32x16_bf16 v[64:79], v[228:231], v[104:107], v[64:79]
	ds_read_b128 v[228:231], v250 offset:256
	s_waitcnt lgkmcnt(5)
	v_mfma_f32_32x32x16_bf16 v[80:95], v[232:235], v[104:107], v[80:95]
	ds_read_b128 v[232:235], v250 offset:13056
	s_waitcnt lgkmcnt(5)
	v_mfma_f32_32x32x16_bf16 v[64:79], v[166:169], v[100:103], v[64:79]
	ds_read_b128 v[166:169], v250 offset:288
	s_waitcnt lgkmcnt(5)
	v_mfma_f32_32x32x16_bf16 v[80:95], v[172:175], v[100:103], v[80:95]
	ds_read_b128 v[172:175], v250 offset:13088
	s_waitcnt lgkmcnt(5)
	v_mfma_f32_32x32x16_bf16 v[64:79], v[176:179], v[96:99], v[64:79]
	ds_read_b128 v[176:179], v250 offset:320
	s_waitcnt lgkmcnt(5)
	v_mfma_f32_32x32x16_bf16 v[80:95], v[222:225], v[96:99], v[80:95]
	ds_read_b128 v[222:225], v250 offset:13120
	s_waitcnt lgkmcnt(5)
	v_mfma_f32_32x32x16_bf16 v[64:79], v[228:231], v[120:123], v[64:79]
	ds_read_b128 v[228:231], v250 offset:352
	s_waitcnt lgkmcnt(5)
	v_mfma_f32_32x32x16_bf16 v[80:95], v[232:235], v[120:123], v[80:95]
	ds_read_b128 v[232:235], v250 offset:13152
	s_waitcnt lgkmcnt(5)
	v_mfma_f32_32x32x16_bf16 v[64:79], v[166:169], v[140:143], v[64:79]
	s_waitcnt lgkmcnt(4)
	v_mfma_f32_32x32x16_bf16 v[80:95], v[172:175], v[140:143], v[80:95]
	s_waitcnt lgkmcnt(3)
	v_mfma_f32_32x32x16_bf16 v[64:79], v[176:179], v[108:111], v[64:79]
	s_waitcnt lgkmcnt(2)
	v_mfma_f32_32x32x16_bf16 v[80:95], v[222:225], v[108:111], v[80:95]
	s_waitcnt lgkmcnt(1)
	v_mfma_f32_32x32x16_bf16 v[64:79], v[228:231], v[136:139], v[64:79]
	s_waitcnt lgkmcnt(0)
	v_mfma_f32_32x32x16_bf16 v[80:95], v[232:235], v[136:139], v[80:95]
	s_setprio 0

.LatB_tail:
	s_cmp_le_i32 s46, s44
	s_cbranch_scc0 .LBB0_32
	s_mov_b32 s5, s13
	s_mul_i32 s38, s5, 43
	s_lshr_b32 s38, s38, 7
	s_mul_i32 s38, s38, 3
	s_sub_i32 s5, s5, s38
	s_mul_i32 s5, s5, 20480
	s_add_i32 s5, s5, 51200
	v_add_u32_e32 v250, s5, v217
	ds_read_b64_tr_b16 v[166:167], v250 offset:0
	ds_read_b64_tr_b16 v[168:169], v250 offset:2560
	ds_read_b64_tr_b16 v[172:173], v250 offset:5120
	ds_read_b64_tr_b16 v[174:175], v250 offset:7680
	ds_read_b64_tr_b16 v[176:177], v250 offset:10240
	ds_read_b64_tr_b16 v[178:179], v250 offset:12800
	ds_read_b64_tr_b16 v[222:223], v250 offset:15360
	ds_read_b64_tr_b16 v[224:225], v250 offset:17920
	ds_read_b64_tr_b16 v[228:229], v250 offset:64
	ds_read_b64_tr_b16 v[230:231], v250 offset:2624
	ds_read_b64_tr_b16 v[232:233], v250 offset:5184
	ds_read_b64_tr_b16 v[234:235], v250 offset:7744
	s_sub_i32 s9, s46, 0
	s_add_i32 s0, s9, 63
	s_cmp_gt_i32 s0, s43
	s_cbranch_scc0 .LatBt_fast
	v_sub_u32_e32 v227, v208, v188
	v_subrev_u32_e32 v227, s9, v227
	v_cmp_gt_i32_e32 vcc, 0, v227
	v_cmp_gt_i32_e64 s[0:1], 1, v227
	v_cmp_gt_i32_e64 s[38:39], 2, v227
	v_cndmask_b32_e32 v64, v64, v226, vcc
	v_cmp_gt_i32_e32 vcc, 3, v227
	v_cndmask_b32_e64 v65, v65, v226, s[0:1]
	v_cmp_gt_i32_e64 s[0:1], 8, v227
	v_cndmask_b32_e64 v66, v66, v226, s[38:39]
	v_cmp_gt_i32_e64 s[38:39], 9, v227
	v_cndmask_b32_e32 v67, v67, v226, vcc
	v_cmp_gt_i32_e32 vcc, 10, v227
	v_cndmask_b32_e64 v68, v68, v226, s[0:1]
	v_cmp_gt_i32_e64 s[0:1], 11, v227
	v_cndmask_b32_e64 v69, v69, v226, s[38:39]
	v_cmp_gt_i32_e64 s[38:39], 16, v227
	v_cndmask_b32_e32 v70, v70, v226, vcc
	v_cmp_gt_i32_e32 vcc, 17, v227
	v_cndmask_b32_e64 v71, v71, v226, s[0:1]
	v_cmp_gt_i32_e64 s[0:1], 18, v227
	v_cndmask_b32_e64 v72, v72, v226, s[38:39]
	v_cmp_gt_i32_e64 s[38:39], 19, v227
	v_cndmask_b32_e32 v73, v73, v226, vcc
	v_cmp_gt_i32_e32 vcc, 24, v227
	v_cndmask_b32_e64 v74, v74, v226, s[0:1]
	v_cmp_gt_i32_e64 s[0:1], 25, v227
	v_cndmask_b32_e64 v75, v75, v226, s[38:39]
	v_cmp_gt_i32_e64 s[38:39], 26, v227
	v_cndmask_b32_e32 v76, v76, v226, vcc
	v_cmp_gt_i32_e32 vcc, 27, v227
	v_cndmask_b32_e64 v77, v77, v226, s[0:1]
	v_cmp_gt_i32_e64 s[0:1], 32, v227
	v_cndmask_b32_e64 v78, v78, v226, s[38:39]
	v_cmp_gt_i32_e64 s[38:39], 33, v227
	v_cndmask_b32_e32 v79, v79, v226, vcc
	v_cmp_gt_i32_e32 vcc, 34, v227
	v_cndmask_b32_e64 v80, v80, v226, s[0:1]
	v_cmp_gt_i32_e64 s[0:1], 35, v227
	v_cndmask_b32_e64 v81, v81, v226, s[38:39]
	v_cmp_gt_i32_e64 s[38:39], 40, v227
	v_cndmask_b32_e32 v82, v82, v226, vcc
	v_cmp_gt_i32_e32 vcc, 41, v227
	v_cndmask_b32_e64 v83, v83, v226, s[0:1]
	v_cmp_gt_i32_e64 s[0:1], 42, v227
	v_cndmask_b32_e64 v84, v84, v226, s[38:39]
	v_cmp_gt_i32_e64 s[38:39], 43, v227
	v_cndmask_b32_e32 v85, v85, v226, vcc
	v_cmp_gt_i32_e32 vcc, 48, v227
	v_cndmask_b32_e64 v86, v86, v226, s[0:1]
	v_cmp_gt_i32_e64 s[0:1], 49, v227
	v_cndmask_b32_e64 v87, v87, v226, s[38:39]
	v_cmp_gt_i32_e64 s[38:39], 50, v227
	v_cndmask_b32_e32 v88, v88, v226, vcc
	v_cmp_gt_i32_e32 vcc, 51, v227
	v_cndmask_b32_e64 v89, v89, v226, s[0:1]
	v_cmp_gt_i32_e64 s[0:1], 56, v227
	v_cndmask_b32_e64 v90, v90, v226, s[38:39]
	v_cmp_gt_i32_e64 s[38:39], 57, v227
	v_cndmask_b32_e32 v91, v91, v226, vcc
	v_cmp_gt_i32_e32 vcc, 58, v227
	v_cndmask_b32_e64 v92, v92, v226, s[0:1]
	v_cmp_gt_i32_e64 s[0:1], 59, v227
	v_cndmask_b32_e64 v93, v93, v226, s[38:39]
	s_nop 1
	v_cndmask_b32_e32 v94, v94, v226, vcc
	v_cndmask_b32_e64 v95, v95, v226, s[0:1]

.LatBt_fast_nr:
	v_fma_f32 v64, v64, s6, -v221
	v_fma_f32 v80, v80, s6, -v221
	v_exp_f32_e32 v64, v64
	v_exp_f32_e32 v80, v80
	v_fma_f32 v65, v65, s6, -v221
	v_fma_f32 v81, v81, s6, -v221
	v_add_f32_e32 v248, v64, v80
	v_exp_f32_e32 v65, v65
	v_exp_f32_e32 v81, v81
	v_mov_b32_e32 v249, v248
	v_fma_f32 v66, v66, s6, -v221
	v_fma_f32 v82, v82, s6, -v221
	v_add_f32_e32 v248, v65, v81
	v_exp_f32_e32 v66, v66
	v_exp_f32_e32 v82, v82
	v_add_f32_e32 v249, v248, v249
	v_fma_f32 v67, v67, s6, -v221
	v_fma_f32 v83, v83, s6, -v221
	v_add_f32_e32 v248, v66, v82
	v_exp_f32_e32 v67, v67
	v_exp_f32_e32 v83, v83
	v_add_f32_e32 v249, v248, v249
	v_fma_f32 v68, v68, s6, -v221
	v_fma_f32 v84, v84, s6, -v221
	v_add_f32_e32 v248, v67, v83
	v_exp_f32_e32 v68, v68
	v_exp_f32_e32 v84, v84
	v_add_f32_e32 v249, v248, v249
	v_fma_f32 v69, v69, s6, -v221
	v_fma_f32 v85, v85, s6, -v221
	v_add_f32_e32 v248, v68, v84
	v_exp_f32_e32 v69, v69
	v_exp_f32_e32 v85, v85
	v_add_f32_e32 v249, v248, v249
	v_fma_f32 v70, v70, s6, -v221
	v_fma_f32 v86, v86, s6, -v221
	v_add_f32_e32 v248, v69, v85
	v_exp_f32_e32 v70, v70
	v_exp_f32_e32 v86, v86
	v_add_f32_e32 v249, v248, v249
	v_fma_f32 v71, v71, s6, -v221
	v_fma_f32 v87, v87, s6, -v221
	v_add_f32_e32 v248, v70, v86
	v_exp_f32_e32 v71, v71
	v_exp_f32_e32 v87, v87
	v_add_f32_e32 v249, v248, v249
	v_fma_f32 v72, v72, s6, -v221
	v_fma_f32 v88, v88, s6, -v221
	v_add_f32_e32 v248, v71, v87
	v_exp_f32_e32 v72, v72
	v_exp_f32_e32 v88, v88
	v_add_f32_e32 v249, v248, v249
	v_fma_f32 v73, v73, s6, -v221
	v_fma_f32 v89, v89, s6, -v221
	v_add_f32_e32 v248, v72, v88
	v_exp_f32_e32 v73, v73
	v_exp_f32_e32 v89, v89
	v_add_f32_e32 v249, v248, v249
	v_fma_f32 v74, v74, s6, -v221
	v_fma_f32 v90, v90, s6, -v221
	v_add_f32_e32 v248, v73, v89
	v_exp_f32_e32 v74, v74
	v_exp_f32_e32 v90, v90
	v_add_f32_e32 v249, v248, v249
	v_fma_f32 v75, v75, s6, -v221
	v_fma_f32 v91, v91, s6, -v221
	v_add_f32_e32 v248, v74, v90
	v_exp_f32_e32 v75, v75
	v_exp_f32_e32 v91, v91
	v_add_f32_e32 v249, v248, v249
	v_fma_f32 v76, v76, s6, -v221
	v_fma_f32 v92, v92, s6, -v221
	v_add_f32_e32 v248, v75, v91
	v_exp_f32_e32 v76, v76
	v_exp_f32_e32 v92, v92
	v_add_f32_e32 v249, v248, v249
	v_fma_f32 v77, v77, s6, -v221
	v_fma_f32 v93, v93, s6, -v221
	v_add_f32_e32 v248, v76, v92
	v_exp_f32_e32 v77, v77
	v_exp_f32_e32 v93, v93
	v_add_f32_e32 v249, v248, v249
	v_fma_f32 v78, v78, s6, -v221
	v_fma_f32 v94, v94, s6, -v221
	v_add_f32_e32 v248, v77, v93
	v_exp_f32_e32 v78, v78
	v_exp_f32_e32 v94, v94
	v_add_f32_e32 v249, v248, v249
	v_fma_f32 v79, v79, s6, -v221
	v_fma_f32 v95, v95, s6, -v221
	v_add_f32_e32 v248, v78, v94
	v_exp_f32_e32 v79, v79
	v_exp_f32_e32 v95, v95
	v_add_f32_e32 v249, v248, v249
	s_nop 0
	v_add_f32_e32 v248, v79, v95
	v_add_f32_e32 v249, v248, v249
	v_fmac_f32_e32 v249, v209, v170
	v_cvt_pk_bf16_f32 v72, v72, v73
	v_cvt_pk_bf16_f32 v73, v74, v75
	v_cvt_pk_bf16_f32 v74, v76, v77
	v_cvt_pk_bf16_f32 v75, v78, v79
	v_cvt_pk_bf16_f32 v76, v64, v65
	v_cvt_pk_bf16_f32 v77, v66, v67
	v_cvt_pk_bf16_f32 v78, v68, v69
	v_cvt_pk_bf16_f32 v79, v70, v71
	v_cvt_pk_bf16_f32 v68, v80, v81
	v_cvt_pk_bf16_f32 v69, v82, v83
	v_cvt_pk_bf16_f32 v70, v84, v85
	v_cvt_pk_bf16_f32 v71, v86, v87
	v_cvt_pk_bf16_f32 v64, v88, v89
	v_cvt_pk_bf16_f32 v65, v90, v91
	v_cvt_pk_bf16_f32 v66, v92, v93
	v_cvt_pk_bf16_f32 v67, v94, v95
	v_mov_b32_e32 v209, v249
	s_nop 1
	s_waitcnt lgkmcnt(10)
	v_mfma_f32_32x32x16_bf16 v[48:63], v[166:169], v[76:79], v[48:63]
	ds_read_b64_tr_b16 v[166:167], v250 offset:10304
	ds_read_b64_tr_b16 v[168:169], v250 offset:12864
	s_waitcnt lgkmcnt(10)
	v_mfma_f32_32x32x16_bf16 v[48:63], v[172:175], v[72:75], v[48:63]
	ds_read_b64_tr_b16 v[172:173], v250 offset:15424
	ds_read_b64_tr_b16 v[174:175], v250 offset:17984
	s_waitcnt lgkmcnt(10)
	v_mfma_f32_32x32x16_bf16 v[48:63], v[176:179], v[68:71], v[48:63]
	ds_read_b64_tr_b16 v[176:177], v250 offset:128
	ds_read_b64_tr_b16 v[178:179], v250 offset:2688
	s_waitcnt lgkmcnt(10)
	v_mfma_f32_32x32x16_bf16 v[48:63], v[222:225], v[64:67], v[48:63]
	ds_read_b64_tr_b16 v[222:223], v250 offset:5248
	ds_read_b64_tr_b16 v[224:225], v250 offset:7808
	s_waitcnt lgkmcnt(10)
	v_mfma_f32_32x32x16_bf16 v[32:47], v[228:231], v[76:79], v[32:47]
	ds_read_b64_tr_b16 v[228:229], v250 offset:10368
	ds_read_b64_tr_b16 v[230:231], v250 offset:12928
	s_waitcnt lgkmcnt(10)
	v_mfma_f32_32x32x16_bf16 v[32:47], v[232:235], v[72:75], v[32:47]
	ds_read_b64_tr_b16 v[232:233], v250 offset:15488
	ds_read_b64_tr_b16 v[234:235], v250 offset:18048
	s_waitcnt lgkmcnt(10)
	v_mfma_f32_32x32x16_bf16 v[32:47], v[166:169], v[68:71], v[32:47]
	ds_read_b64_tr_b16 v[166:167], v250 offset:192
	ds_read_b64_tr_b16 v[168:169], v250 offset:2752
	s_waitcnt lgkmcnt(10)
	v_mfma_f32_32x32x16_bf16 v[32:47], v[172:175], v[64:67], v[32:47]
	ds_read_b64_tr_b16 v[172:173], v250 offset:5312
	ds_read_b64_tr_b16 v[174:175], v250 offset:7872
	s_waitcnt lgkmcnt(10)
	v_mfma_f32_32x32x16_bf16 v[16:31], v[176:179], v[76:79], v[16:31]
	ds_read_b64_tr_b16 v[176:177], v250 offset:10432
	ds_read_b64_tr_b16 v[178:179], v250 offset:12992
	s_waitcnt lgkmcnt(10)
	v_mfma_f32_32x32x16_bf16 v[16:31], v[222:225], v[72:75], v[16:31]
	ds_read_b64_tr_b16 v[222:223], v250 offset:15552
	ds_read_b64_tr_b16 v[224:225], v250 offset:18112
	s_waitcnt lgkmcnt(10)
	v_mfma_f32_32x32x16_bf16 v[16:31], v[228:231], v[68:71], v[16:31]
	s_waitcnt lgkmcnt(8)
	v_mfma_f32_32x32x16_bf16 v[16:31], v[232:235], v[64:67], v[16:31]
	s_waitcnt lgkmcnt(6)
	v_mfma_f32_32x32x16_bf16 v[0:15], v[166:169], v[76:79], v[0:15]
	s_waitcnt lgkmcnt(4)
	v_mfma_f32_32x32x16_bf16 v[0:15], v[172:175], v[72:75], v[0:15]
	s_waitcnt lgkmcnt(2)
	v_mfma_f32_32x32x16_bf16 v[0:15], v[176:179], v[68:71], v[0:15]
	s_waitcnt lgkmcnt(0)
	v_mfma_f32_32x32x16_bf16 v[0:15], v[222:225], v[64:67], v[0:15]
	v_mov_b32_e32 v247, v221
	s_branch .LBB0_32
